# v14 + GLA output unit: all 24 fragment loads in flight together, MFMAs behind counted vmcnt waits
# speedup vs baseline: 1.0086x; 1.0086x over previous
.LBB0_617:
	v_mov_b32_e32 v0, v1
	s_ashr_i32 s12, s0, 2
	v_mbcnt_lo_u32_b32 v0, -1, v0
	v_mbcnt_hi_u32_b32 v0, -1, v0
	s_ashr_i32 s13, s12, 31
	v_add_u32_e32 v58, s54, v0
	s_lshl_b64 s[18:19], s[12:13], 8
	s_lshl_b64 s[12:13], s[12:13], 6
	s_and_b32 s1, s0, 3
	v_readfirstlane_b32 s20, v58
	v_and_b32_e32 v65, 31, v58
	v_mov_b32_e32 v3, s13
	s_ashr_i32 s20, s20, 1
	v_or_b32_e32 v2, s12, v65
	s_lshl_b32 s86, s1, 8
	s_andn2_b32 s20, s20, 31
	v_lshlrev_b64 v[4:5], 13, v[2:3]
	v_or_b32_e32 v2, 32, v2
	s_add_i32 s21, s20, s86
	v_lshlrev_b64 v[2:3], 13, v[2:3]
	v_bfe_u32 v66, v58, 5, 1
	v_lshl_add_u64 v[4:5], s[8:9], 0, v[4:5]
	v_or_b32_e32 v6, s21, v65
	v_lshl_add_u64 v[2:3], s[8:9], 0, v[2:3]
	v_lshlrev_b32_e32 v0, 4, v66
	v_lshl_add_u64 v[4:5], v[4:5], 0, s[86:87]
	v_ashrrev_i32_e32 v7, 31, v6
	v_lshl_add_u64 v[8:9], v[2:3], 0, s[86:87]
	v_lshl_add_u64 v[54:55], v[4:5], 0, v[0:1]
	v_lshlrev_b64 v[6:7], 16, v[6:7]
	v_lshl_add_u64 v[56:57], v[8:9], 0, v[0:1]
	v_lshl_add_u64 v[10:11], s[10:11], 0, v[6:7]
	v_lshl_add_u64 v[10:11], v[10:11], 0, s[18:19]
	v_lshl_add_u64 v[62:63], v[10:11], 0, v[0:1]
	global_load_dwordx4 v[100:103], v[54:55], off offset:1664
	global_load_dwordx4 v[104:107], v[54:55], off offset:1696
	global_load_dwordx4 v[108:111], v[56:57], off offset:1664
	global_load_dwordx4 v[112:115], v[62:63], off
	global_load_dwordx4 v[116:119], v[62:63], off offset:32
	global_load_dwordx4 v[120:123], v[56:57], off offset:1696
	global_load_dwordx4 v[124:127], v[54:55], off offset:1728
	global_load_dwordx4 v[128:131], v[54:55], off offset:1760
	global_load_dwordx4 v[132:135], v[56:57], off offset:1728
	global_load_dwordx4 v[136:139], v[62:63], off offset:64
	global_load_dwordx4 v[140:143], v[62:63], off offset:96
	global_load_dwordx4 v[144:147], v[56:57], off offset:1760
	global_load_dwordx4 v[148:151], v[54:55], off offset:1792
	global_load_dwordx4 v[152:155], v[54:55], off offset:1824
	global_load_dwordx4 v[156:159], v[56:57], off offset:1792
	global_load_dwordx4 v[160:163], v[62:63], off offset:128
	global_load_dwordx4 v[164:167], v[62:63], off offset:160
	global_load_dwordx4 v[168:171], v[56:57], off offset:1824
	global_load_dwordx4 v[172:175], v[54:55], off offset:1856
	global_load_dwordx4 v[176:179], v[54:55], off offset:1888
	global_load_dwordx4 v[180:183], v[56:57], off offset:1856
	global_load_dwordx4 v[184:187], v[62:63], off offset:192
	global_load_dwordx4 v[188:191], v[62:63], off offset:224
	global_load_dwordx4 v[192:195], v[56:57], off offset:1888
	v_and_b32_e32 v46, 64, v233
	v_add_u32_e32 v61, 64, v46
	v_xor_b32_e32 v0, 1, v233
	v_xor_b32_e32 v59, 2, v233
	v_cmp_lt_i32_e32 vcc, v0, v61
	v_xor_b32_e32 v60, 4, v233
	s_movk_i32 s21, 0x410
	v_cndmask_b32_e32 v0, v233, v0, vcc
	v_cmp_lt_i32_e32 vcc, v59, v61
	v_ashrrev_i32_e32 v64, 3, v58
	v_lshlrev_b32_e32 v70, 2, v65
	v_ashrrev_i32_e32 v65, 31, v64
	v_mul_u32_u24_e32 v71, 0x1040, v66
	s_lshl_b32 s86, s1, 9
	s_mov_b64 s[18:19], 0x16a0
	s_add_i32 s0, s0, s30
	s_waitcnt vmcnt(20)
	v_mfma_f32_32x32x16_bf16 v[18:33], v[100:103], v[112:115], 0
	s_waitcnt vmcnt(20)
	v_mfma_f32_32x32x16_bf16 v[2:17], v[108:111], v[112:115], 0
	s_waitcnt vmcnt(19)
	v_mfma_f32_32x32x16_bf16 v[18:33], v[104:107], v[116:119], v[18:33]
	s_waitcnt vmcnt(18)
	v_mfma_f32_32x32x16_bf16 v[2:17], v[120:123], v[116:119], v[2:17]
	s_waitcnt vmcnt(14)
	v_mfma_f32_32x32x16_bf16 v[18:33], v[124:127], v[136:139], v[18:33]
	s_waitcnt vmcnt(14)
	v_mfma_f32_32x32x16_bf16 v[2:17], v[132:135], v[136:139], v[2:17]
	v_cndmask_b32_e32 v38, v233, v59, vcc
	v_cmp_lt_i32_e32 vcc, v60, v61
	v_lshlrev_b32_e32 v59, 2, v38
	v_lshlrev_b32_e32 v61, 2, v0
	v_cndmask_b32_e32 v39, v233, v60, vcc
	v_lshlrev_b32_e32 v60, 2, v39
	v_and_b32_e32 v0, 7, v58
	s_waitcnt vmcnt(13)
	v_mfma_f32_32x32x16_bf16 v[18:33], v[128:131], v[140:143], v[18:33]
	v_lshlrev_b32_e32 v58, 5, v0
	v_lshlrev_b32_e32 v0, 4, v0
	s_waitcnt vmcnt(12)
	v_mfma_f32_32x32x16_bf16 v[2:17], v[144:147], v[140:143], v[2:17]
	s_waitcnt vmcnt(8)
	v_mfma_f32_32x32x16_bf16 v[18:33], v[148:151], v[160:163], v[18:33]
	s_waitcnt vmcnt(8)
	v_mfma_f32_32x32x16_bf16 v[2:17], v[156:159], v[160:163], v[2:17]
	v_mul_lo_u32 v34, v64, s21
	v_add3_u32 v72, 0, v34, v58
	v_lshl_add_u64 v[34:35], s[12:13], 0, v[64:65]
	v_lshlrev_b64 v[36:37], 13, v[34:35]
	v_lshlrev_b64 v[66:67], 12, v[34:35]
	v_lshl_add_u64 v[68:69], s[8:9], 0, v[36:37]
	s_lshl_b32 s12, s20, 2
	s_waitcnt vmcnt(7)
	v_mfma_f32_32x32x16_bf16 v[18:33], v[152:155], v[164:167], v[18:33]
	s_add_i32 s12, s12, 0
	s_cmpk_gt_i32 s0, 0x3ff
	s_waitcnt vmcnt(6)
	v_mfma_f32_32x32x16_bf16 v[2:17], v[168:171], v[164:167], v[2:17]
	s_nop 0
	v_add3_u32 v44, s12, v70, v71
	s_waitcnt vmcnt(2)
	v_mfma_f32_32x32x16_bf16 v[18:33], v[172:175], v[184:187], v[18:33]
	s_waitcnt vmcnt(2)
	v_mfma_f32_32x32x16_bf16 v[2:17], v[180:183], v[184:187], v[2:17]
	v_lshl_add_u64 v[38:39], s[16:17], 0, v[66:67]
	v_lshl_add_u64 v[40:41], v[68:69], 0, s[86:87]
	v_lshl_add_u64 v[38:39], v[38:39], 0, s[86:87]
	v_lshl_add_u64 v[40:41], v[40:41], 0, v[0:1]
	v_lshl_add_u64 v[54:55], v[38:39], 0, v[0:1]
	v_add_co_u32_e32 v42, vcc, s91, v40
	s_waitcnt vmcnt(1)
	v_mfma_f32_32x32x16_bf16 v[18:33], v[176:179], v[188:191], v[18:33]
	v_addc_co_u32_e32 v43, vcc, 0, v41, vcc
	v_lshl_add_u64 v[56:57], v[40:41], 0, s[18:19]
	s_waitcnt vmcnt(0)
	v_mfma_f32_32x32x16_bf16 v[2:17], v[192:195], v[188:191], v[2:17]
	s_nop 7
	v_mul_f32_e32 v0, 0x3db504f3, v18
	v_mul_f32_e32 v18, 0x3db504f3, v19
	v_mul_f32_e32 v19, 0x3db504f3, v20
	v_mul_f32_e32 v20, 0x3db504f3, v21
	v_mul_f32_e32 v21, 0x3db504f3, v22
	v_mul_f32_e32 v22, 0x3db504f3, v23
	v_mul_f32_e32 v23, 0x3db504f3, v24
	v_mul_f32_e32 v24, 0x3db504f3, v25
	v_mul_f32_e32 v25, 0x3db504f3, v26
	v_mul_f32_e32 v26, 0x3db504f3, v27
	v_mul_f32_e32 v27, 0x3db504f3, v28
	v_mul_f32_e32 v28, 0x3db504f3, v29
	v_mul_f32_e32 v29, 0x3db504f3, v30
	v_mul_f32_e32 v30, 0x3db504f3, v31
	v_mul_f32_e32 v31, 0x3db504f3, v32
	v_mul_f32_e32 v32, 0x3db504f3, v33
	ds_write_b32 v44, v0
	ds_write_b32 v44, v18 offset:1040
	ds_write_b32 v44, v19 offset:2080
	ds_write_b32 v44, v20 offset:3120
	ds_write_b32 v44, v21 offset:8320
	ds_write_b32 v44, v22 offset:9360
	ds_write_b32 v44, v23 offset:10400
	ds_write_b32 v44, v24 offset:11440
	ds_write_b32 v44, v25 offset:16640
	ds_write_b32 v44, v26 offset:17680
	ds_write_b32 v44, v27 offset:18720
	ds_write_b32 v44, v28 offset:19760
	ds_write_b32 v44, v29 offset:24960
	ds_write_b32 v44, v30 offset:26000
	ds_write_b32 v44, v31 offset:27040
	ds_write_b32 v44, v32 offset:28080
	v_mul_f32_e32 v0, 0x3db504f3, v2
	v_mul_f32_e32 v2, 0x3db504f3, v3
	v_mul_f32_e32 v3, 0x3db504f3, v4
	v_mul_f32_e32 v4, 0x3db504f3, v5
	v_mul_f32_e32 v5, 0x3db504f3, v6
	v_mul_f32_e32 v6, 0x3db504f3, v7
	v_mul_f32_e32 v7, 0x3db504f3, v8
	v_mul_f32_e32 v8, 0x3db504f3, v9
	v_mul_f32_e32 v9, 0x3db504f3, v10
	v_mul_f32_e32 v10, 0x3db504f3, v11
	v_mul_f32_e32 v11, 0x3db504f3, v12
	v_mul_f32_e32 v12, 0x3db504f3, v13
	v_mul_f32_e32 v13, 0x3db504f3, v14
	v_mul_f32_e32 v14, 0x3db504f3, v15
	v_mul_f32_e32 v15, 0x3db504f3, v16
	v_mul_f32_e32 v16, 0x3db504f3, v17
	ds_write_b32 v44, v0 offset:33280
	ds_write_b32 v44, v2 offset:34320
	ds_write_b32 v44, v3 offset:35360
	ds_write_b32 v44, v4 offset:36400
	ds_write_b32 v44, v5 offset:41600
	ds_write_b32 v44, v6 offset:42640
	ds_write_b32 v44, v7 offset:43680
	ds_write_b32 v44, v8 offset:44720
	ds_write_b32 v44, v9 offset:49920
	ds_write_b32 v44, v10 offset:50960
	ds_write_b32 v44, v11 offset:52000
	ds_write_b32 v44, v12 offset:53040
	ds_write_b32 v44, v13 offset:58240
	ds_write_b32 v44, v14 offset:59280
	ds_write_b32 v44, v15 offset:60320
	ds_write_b32 v44, v16 offset:61360
	s_waitcnt lgkmcnt(0)
	s_barrier
	ds_read_b128 v[30:33], v72
	ds_read_b128 v[26:29], v72 offset:16
	ds_read_b128 v[22:25], v72 offset:256
	ds_read_b128 v[18:21], v72 offset:272
	ds_read_b128 v[14:17], v72 offset:512
	ds_read_b128 v[10:13], v72 offset:528
	ds_read_b128 v[6:9], v72 offset:768
	ds_read_b128 v[2:5], v72 offset:784
	global_load_dwordx4 v[34:37], v58, s[6:7] offset:16
	global_load_dwordx4 v[38:41], v58, s[6:7]
	global_load_dwordx4 v[46:49], v[56:57], off offset:128
	global_load_dwordx4 v[50:53], v[42:43], off offset:1696
	s_nop 0
	global_load_dwordx4 v[42:45], v[56:57], off offset:384
	s_waitcnt lgkmcnt(7)
	v_mov_b32_e32 v64, v31
	s_waitcnt lgkmcnt(6)
	v_mov_b32_e32 v65, v27
	v_mov_b32_e32 v68, v33
	v_mov_b32_e32 v69, v29
	v_mov_b32_e32 v62, v30
	v_mov_b32_e32 v63, v26
	v_mov_b32_e32 v66, v32
	v_mov_b32_e32 v67, v28
	s_waitcnt lgkmcnt(5)
	v_pk_mul_f32 v[70:71], v[24:25], v[24:25]
	v_pk_mul_f32 v[72:73], v[22:23], v[22:23]
	v_pk_mul_f32 v[64:65], v[64:65], v[64:65]
	v_pk_mul_f32 v[68:69], v[68:69], v[68:69]
	v_pk_mov_b32 v[84:85], v[72:73], v[70:71] op_sel:[1,0]
	v_mov_b32_e32 v73, v71
	v_pk_fma_f32 v[62:63], v[62:63], v[62:63], v[64:65]
	v_pk_fma_f32 v[64:65], v[66:67], v[66:67], v[68:69]
	s_waitcnt lgkmcnt(4)
	v_mul_f32_e32 v0, v19, v19
	v_mul_f32_e32 v74, v21, v21
	v_pk_add_f32 v[66:67], v[84:85], v[72:73]
	v_pk_add_f32 v[62:63], v[62:63], v[64:65]
	s_waitcnt lgkmcnt(3)
	v_mul_f32_e32 v83, v14, v14
	v_mul_f32_e32 v88, v15, v15
	v_mul_f32_e32 v89, v16, v16
	v_mul_f32_e32 v90, v17, v17
	v_pk_fma_f32 v[70:71], v[18:19], v[18:19], v[0:1] op_sel_hi:[1,1,0]
	v_pk_fma_f32 v[74:75], v[20:21], v[20:21], v[74:75] op_sel_hi:[1,1,0]
	v_pk_add_f32 v[64:65], v[66:67], v[66:67] op_sel:[0,1] op_sel_hi:[1,0]
	v_pk_add_f32 v[62:63], v[62:63], v[62:63] op_sel:[0,1] op_sel_hi:[1,0]
	s_waitcnt lgkmcnt(2)
	v_pk_mul_f32 v[76:77], v[12:13], v[12:13]
	v_pk_mul_f32 v[78:79], v[10:11], v[10:11]
	v_mov_b32_e32 v71, v89
	v_mov_b32_e32 v75, v90
	v_mov_b32_e32 v65, v88
	v_mov_b32_e32 v63, v83
	v_pk_mov_b32 v[86:87], v[78:79], v[76:77] op_sel:[1,0]
	v_mov_b32_e32 v79, v77
	v_pk_add_f32 v[66:67], v[70:71], v[74:75]
	v_pk_add_f32 v[62:63], v[62:63], v[64:65]
	s_waitcnt lgkmcnt(1)
	v_mul_f32_e32 v80, v7, v7
	v_mul_f32_e32 v82, v9, v9
	v_pk_add_f32 v[68:69], v[86:87], v[78:79]
	v_pk_add_f32 v[62:63], v[62:63], v[66:67]
	s_waitcnt lgkmcnt(0)
	v_mul_f32_e32 v91, v2, v2
	v_mul_f32_e32 v92, v3, v3
	v_mul_f32_e32 v93, v4, v4
	v_mul_f32_e32 v94, v5, v5
	v_pk_fma_f32 v[76:77], v[6:7], v[6:7], v[80:81] op_sel_hi:[1,1,0]
	v_pk_fma_f32 v[80:81], v[8:9], v[8:9], v[82:83] op_sel_hi:[1,1,0]
	v_pk_add_f32 v[68:69], v[68:69], v[68:69] op_sel:[0,1] op_sel_hi:[1,0]
	v_pk_add_f32 v[62:63], v[62:63], v[62:63] op_sel:[0,1] op_sel_hi:[1,0]
	v_mov_b32_e32 v77, v93
	v_mov_b32_e32 v81, v94
	v_mov_b32_e32 v69, v92
	v_mov_b32_e32 v63, v91
	v_pk_add_f32 v[70:71], v[76:77], v[80:81]
	v_pk_add_f32 v[62:63], v[62:63], v[68:69]
	s_nop 0
	v_pk_add_f32 v[62:63], v[62:63], v[70:71]
	s_nop 0
	v_add_f32_e32 v0, v62, v63
	ds_bpermute_b32 v61, v61, v0
	s_waitcnt lgkmcnt(0)
	v_add_f32_e32 v0, v0, v61
	ds_bpermute_b32 v59, v59, v0
	s_waitcnt lgkmcnt(0)
	v_add_f32_e32 v0, v0, v59
	ds_bpermute_b32 v59, v60, v0
	s_waitcnt lgkmcnt(0)
	v_add_f32_e32 v0, v0, v59
	v_fmamk_f32 v0, v0, 0x3b800000, v232
	v_mul_f32_e32 v59, 0x4b800000, v0
	v_cmp_gt_f32_e32 vcc, s5, v0
	s_waitcnt vmcnt(1)
	v_lshlrev_b32_e32 v60, 16, v50
	v_and_b32_e32 v61, 0xffff0000, v50
	v_cndmask_b32_e32 v0, v0, v59, vcc
	v_rsq_f32_e32 v0, v0
	s_nop 0
	v_mul_f32_e32 v59, 0x45800000, v0
	v_cndmask_b32_e32 v0, v0, v59, vcc
	v_pk_mul_f32 v[30:31], v[30:31], v[0:1] op_sel_hi:[1,0]
	v_pk_mul_f32 v[32:33], v[32:33], v[0:1] op_sel_hi:[1,0]
	v_pk_mul_f32 v[26:27], v[26:27], v[0:1] op_sel_hi:[1,0]
	v_pk_mul_f32 v[28:29], v[28:29], v[0:1] op_sel_hi:[1,0]
	v_pk_mul_f32 v[30:31], v[38:39], v[30:31]
	v_lshlrev_b32_e32 v38, 16, v51
	v_and_b32_e32 v39, 0xffff0000, v51
	v_pk_mul_f32 v[32:33], v[40:41], v[32:33]
	v_lshlrev_b32_e32 v40, 16, v52
	v_and_b32_e32 v41, 0xffff0000, v52
	v_pk_mul_f32 v[26:27], v[34:35], v[26:27]
	v_lshlrev_b32_e32 v34, 16, v53
	v_and_b32_e32 v35, 0xffff0000, v53
	v_pk_mul_f32 v[28:29], v[36:37], v[28:29]
	v_mul_f32_e32 v36, 0xbfb8aa3b, v60
	v_mul_f32_e32 v37, 0xbfb8aa3b, v61
	v_mul_f32_e32 v50, 0xbfb8aa3b, v38
	v_mul_f32_e32 v51, 0xbfb8aa3b, v39
	v_mul_f32_e32 v52, 0xbfb8aa3b, v40
	v_mul_f32_e32 v53, 0xbfb8aa3b, v41
	v_mul_f32_e32 v59, 0xbfb8aa3b, v34
	v_mul_f32_e32 v62, 0xbfb8aa3b, v35
	v_exp_f32_e32 v36, v36
	v_exp_f32_e32 v37, v37
	v_exp_f32_e32 v50, v50
	v_exp_f32_e32 v51, v51
	v_exp_f32_e32 v52, v52
	v_exp_f32_e32 v53, v53
	v_exp_f32_e32 v59, v59
	v_exp_f32_e32 v62, v62
	v_add_f32_e32 v36, 1.0, v36
	v_add_f32_e32 v37, 1.0, v37
	v_add_f32_e32 v50, 1.0, v50
	v_add_f32_e32 v51, 1.0, v51
	v_add_f32_e32 v52, 1.0, v52
	v_add_f32_e32 v53, 1.0, v53
	v_add_f32_e32 v59, 1.0, v59
	v_add_f32_e32 v63, 1.0, v62
	v_rcp_f32_e32 v36, v36
	v_rcp_f32_e32 v37, v37
	v_rcp_f32_e32 v50, v50
	v_rcp_f32_e32 v51, v51
	v_rcp_f32_e32 v52, v52
	v_rcp_f32_e32 v53, v53
	v_rcp_f32_e32 v62, v59
	v_rcp_f32_e32 v63, v63
	v_pk_mul_f32 v[36:37], v[36:37], v[60:61]
	v_pk_mul_f32 v[38:39], v[50:51], v[38:39]
	v_pk_mul_f32 v[40:41], v[52:53], v[40:41]
	v_pk_mul_f32 v[34:35], v[62:63], v[34:35]
	v_pk_mul_f32 v[30:31], v[36:37], v[30:31]
	v_pk_mul_f32 v[32:33], v[38:39], v[32:33]
	v_pk_mul_f32 v[36:37], v[40:41], v[26:27]
	v_pk_mul_f32 v[34:35], v[34:35], v[28:29]
	v_cvt_pk_bf16_f32 v26, v30, v31
	v_cvt_pk_bf16_f32 v27, v32, v33
	v_cvt_pk_bf16_f32 v28, v36, v37
	v_cvt_pk_bf16_f32 v29, v34, v35
	global_store_dwordx4 v[54:55], v[26:29], off offset:2048
	global_load_dwordx4 v[30:33], v58, s[6:7] offset:256
	global_load_dwordx4 v[34:37], v58, s[6:7] offset:272
	s_nop 0
	global_load_dwordx4 v[26:29], v[56:57], off offset:256
	v_lshlrev_b32_e32 v38, 16, v46
	v_and_b32_e32 v39, 0xffff0000, v46
	v_lshlrev_b32_e32 v40, 16, v47
	v_and_b32_e32 v41, 0xffff0000, v47
	v_lshlrev_b32_e32 v46, 16, v48
	v_and_b32_e32 v47, 0xffff0000, v48
	v_lshlrev_b32_e32 v48, 16, v49
	v_and_b32_e32 v49, 0xffff0000, v49
	v_mul_f32_e32 v50, 0xbfb8aa3b, v38
	v_mul_f32_e32 v51, 0xbfb8aa3b, v39
	v_mul_f32_e32 v52, 0xbfb8aa3b, v40
	v_mul_f32_e32 v53, 0xbfb8aa3b, v41
	v_mul_f32_e32 v56, 0xbfb8aa3b, v46
	v_mul_f32_e32 v57, 0xbfb8aa3b, v47
	v_mul_f32_e32 v59, 0xbfb8aa3b, v48
	v_mul_f32_e32 v60, 0xbfb8aa3b, v49
	v_exp_f32_e32 v50, v50
	v_exp_f32_e32 v51, v51
	v_exp_f32_e32 v52, v52
	v_exp_f32_e32 v53, v53
	v_exp_f32_e32 v56, v56
	v_exp_f32_e32 v57, v57
	v_exp_f32_e32 v59, v59
	v_exp_f32_e32 v60, v60
	v_add_f32_e32 v50, 1.0, v50
	v_add_f32_e32 v51, 1.0, v51
	v_add_f32_e32 v52, 1.0, v52
	v_add_f32_e32 v53, 1.0, v53
	v_add_f32_e32 v56, 1.0, v56
	v_add_f32_e32 v57, 1.0, v57
	v_add_f32_e32 v59, 1.0, v59
	v_add_f32_e32 v61, 1.0, v60
	v_rcp_f32_e32 v50, v50
	v_rcp_f32_e32 v51, v51
	v_rcp_f32_e32 v52, v52
	v_rcp_f32_e32 v53, v53
	v_rcp_f32_e32 v56, v56
	v_rcp_f32_e32 v57, v57
	v_rcp_f32_e32 v60, v59
	v_rcp_f32_e32 v61, v61
	v_pk_mul_f32 v[22:23], v[22:23], v[0:1] op_sel_hi:[1,0]
	v_pk_mul_f32 v[24:25], v[24:25], v[0:1] op_sel_hi:[1,0]
	v_pk_mul_f32 v[18:19], v[18:19], v[0:1] op_sel_hi:[1,0]
	v_pk_mul_f32 v[20:21], v[20:21], v[0:1] op_sel_hi:[1,0]
	v_pk_mul_f32 v[38:39], v[50:51], v[38:39]
	v_pk_mul_f32 v[40:41], v[52:53], v[40:41]
	v_pk_mul_f32 v[46:47], v[56:57], v[46:47]
	v_pk_mul_f32 v[48:49], v[60:61], v[48:49]
	v_pk_mul_f32 v[14:15], v[14:15], v[0:1] op_sel_hi:[1,0]
	v_pk_mul_f32 v[16:17], v[16:17], v[0:1] op_sel_hi:[1,0]
	v_pk_mul_f32 v[10:11], v[10:11], v[0:1] op_sel_hi:[1,0]
	v_pk_mul_f32 v[12:13], v[12:13], v[0:1] op_sel_hi:[1,0]
	v_pk_mul_f32 v[6:7], v[6:7], v[0:1] op_sel_hi:[1,0]
	v_pk_mul_f32 v[8:9], v[8:9], v[0:1] op_sel_hi:[1,0]
	v_pk_mul_f32 v[2:3], v[2:3], v[0:1] op_sel_hi:[1,0]
	v_pk_mul_f32 v[4:5], v[4:5], v[0:1] op_sel_hi:[1,0]
	s_waitcnt vmcnt(2)
	v_pk_mul_f32 v[22:23], v[30:31], v[22:23]
	v_pk_mul_f32 v[24:25], v[32:33], v[24:25]
	s_waitcnt vmcnt(1)
	v_pk_mul_f32 v[18:19], v[34:35], v[18:19]
	v_pk_mul_f32 v[20:21], v[36:37], v[20:21]
	v_pk_mul_f32 v[22:23], v[22:23], v[38:39]
	v_pk_mul_f32 v[24:25], v[24:25], v[40:41]
	v_pk_mul_f32 v[30:31], v[18:19], v[46:47]
	v_pk_mul_f32 v[32:33], v[20:21], v[48:49]
	v_cvt_pk_bf16_f32 v18, v22, v23
	v_cvt_pk_bf16_f32 v19, v24, v25
	v_cvt_pk_bf16_f32 v20, v30, v31
	v_cvt_pk_bf16_f32 v21, v32, v33
	global_store_dwordx4 v[54:55], v[18:21], off offset:2176
	global_load_dwordx4 v[18:21], v58, s[6:7] offset:512
	s_nop 0
	global_load_dwordx4 v[22:25], v58, s[6:7] offset:528
	s_waitcnt vmcnt(3)
	v_lshlrev_b32_e32 v30, 16, v26
	v_and_b32_e32 v31, 0xffff0000, v26
	v_lshlrev_b32_e32 v26, 16, v27
	v_and_b32_e32 v27, 0xffff0000, v27
	v_lshlrev_b32_e32 v32, 16, v28
	v_and_b32_e32 v33, 0xffff0000, v28
	v_lshlrev_b32_e32 v28, 16, v29
	v_and_b32_e32 v29, 0xffff0000, v29
	v_mul_f32_e32 v34, 0xbfb8aa3b, v30
	v_mul_f32_e32 v35, 0xbfb8aa3b, v31
	v_mul_f32_e32 v36, 0xbfb8aa3b, v26
	v_mul_f32_e32 v37, 0xbfb8aa3b, v27
	v_mul_f32_e32 v38, 0xbfb8aa3b, v32
	v_mul_f32_e32 v39, 0xbfb8aa3b, v33
	v_mul_f32_e32 v40, 0xbfb8aa3b, v28
	v_mul_f32_e32 v41, 0xbfb8aa3b, v29
	v_exp_f32_e32 v34, v34
	v_exp_f32_e32 v35, v35
	v_exp_f32_e32 v36, v36
	v_exp_f32_e32 v37, v37
	v_exp_f32_e32 v38, v38
	v_exp_f32_e32 v39, v39
	v_exp_f32_e32 v40, v40
	v_exp_f32_e32 v41, v41
	v_add_f32_e32 v34, 1.0, v34
	v_add_f32_e32 v35, 1.0, v35
	v_add_f32_e32 v36, 1.0, v36
	v_add_f32_e32 v37, 1.0, v37
	v_add_f32_e32 v38, 1.0, v38
	v_add_f32_e32 v39, 1.0, v39
	v_add_f32_e32 v40, 1.0, v40
	v_add_f32_e32 v41, 1.0, v41
	v_rcp_f32_e32 v34, v34
	v_rcp_f32_e32 v35, v35
	v_rcp_f32_e32 v36, v36
	v_rcp_f32_e32 v37, v37
	v_rcp_f32_e32 v38, v38
	v_rcp_f32_e32 v39, v39
	v_rcp_f32_e32 v40, v40
	v_rcp_f32_e32 v41, v41
	v_pk_mul_f32 v[30:31], v[34:35], v[30:31]
	v_pk_mul_f32 v[26:27], v[36:37], v[26:27]
	v_pk_mul_f32 v[32:33], v[38:39], v[32:33]
	v_pk_mul_f32 v[28:29], v[40:41], v[28:29]
	s_waitcnt vmcnt(1)
	v_pk_mul_f32 v[14:15], v[18:19], v[14:15]
	v_pk_mul_f32 v[16:17], v[20:21], v[16:17]
	s_waitcnt vmcnt(0)
	v_pk_mul_f32 v[10:11], v[22:23], v[10:11]
	v_pk_mul_f32 v[12:13], v[24:25], v[12:13]
	v_pk_mul_f32 v[14:15], v[14:15], v[30:31]
	v_pk_mul_f32 v[16:17], v[16:17], v[26:27]
	v_pk_mul_f32 v[18:19], v[10:11], v[32:33]
	v_pk_mul_f32 v[20:21], v[12:13], v[28:29]
	v_cvt_pk_bf16_f32 v10, v14, v15
	v_cvt_pk_bf16_f32 v11, v16, v17
	v_cvt_pk_bf16_f32 v12, v18, v19
	v_cvt_pk_bf16_f32 v13, v20, v21
	global_store_dwordx4 v[54:55], v[10:13], off offset:2304
	global_load_dwordx4 v[10:13], v58, s[6:7] offset:768
	s_nop 0
	global_load_dwordx4 v[14:17], v58, s[6:7] offset:784
	v_lshlrev_b32_e32 v18, 16, v42
	v_and_b32_e32 v19, 0xffff0000, v42
	v_lshlrev_b32_e32 v20, 16, v43
	v_and_b32_e32 v21, 0xffff0000, v43
	v_lshlrev_b32_e32 v22, 16, v44
	v_and_b32_e32 v23, 0xffff0000, v44
	v_lshlrev_b32_e32 v24, 16, v45
	v_and_b32_e32 v25, 0xffff0000, v45
	v_mul_f32_e32 v0, 0xbfb8aa3b, v18
	v_mul_f32_e32 v26, 0xbfb8aa3b, v19
	v_mul_f32_e32 v27, 0xbfb8aa3b, v20
	v_mul_f32_e32 v28, 0xbfb8aa3b, v21
	v_mul_f32_e32 v29, 0xbfb8aa3b, v22
	v_mul_f32_e32 v30, 0xbfb8aa3b, v23
	v_mul_f32_e32 v31, 0xbfb8aa3b, v24
	v_mul_f32_e32 v32, 0xbfb8aa3b, v25
	v_exp_f32_e32 v0, v0
	v_exp_f32_e32 v26, v26
	v_exp_f32_e32 v27, v27
	v_exp_f32_e32 v28, v28
	v_exp_f32_e32 v29, v29
	v_exp_f32_e32 v30, v30
	v_exp_f32_e32 v31, v31
	v_exp_f32_e32 v32, v32
	v_add_f32_e32 v0, 1.0, v0
	v_add_f32_e32 v33, 1.0, v26
	v_add_f32_e32 v34, 1.0, v27
	v_add_f32_e32 v35, 1.0, v28
	v_add_f32_e32 v36, 1.0, v29
	v_add_f32_e32 v37, 1.0, v30
	v_add_f32_e32 v38, 1.0, v31
	v_add_f32_e32 v39, 1.0, v32
	v_rcp_f32_e32 v26, v0
	v_rcp_f32_e32 v27, v33
	v_rcp_f32_e32 v28, v34
	v_rcp_f32_e32 v29, v35
	v_rcp_f32_e32 v30, v36
	v_rcp_f32_e32 v31, v37
	v_rcp_f32_e32 v32, v38
	v_rcp_f32_e32 v33, v39
	v_pk_mul_f32 v[18:19], v[26:27], v[18:19]
	v_pk_mul_f32 v[20:21], v[28:29], v[20:21]
	v_pk_mul_f32 v[22:23], v[30:31], v[22:23]
	v_pk_mul_f32 v[24:25], v[32:33], v[24:25]
	s_waitcnt vmcnt(1)
	v_pk_mul_f32 v[6:7], v[6:7], v[10:11]
	v_pk_mul_f32 v[8:9], v[8:9], v[12:13]
	s_waitcnt vmcnt(0)
	v_pk_mul_f32 v[2:3], v[2:3], v[14:15]
	v_pk_mul_f32 v[4:5], v[4:5], v[16:17]
	v_pk_mul_f32 v[6:7], v[6:7], v[18:19]
	v_pk_mul_f32 v[8:9], v[8:9], v[20:21]
	v_pk_mul_f32 v[10:11], v[2:3], v[22:23]
	v_pk_mul_f32 v[12:13], v[4:5], v[24:25]
	v_cvt_pk_bf16_f32 v2, v6, v7
	v_cvt_pk_bf16_f32 v3, v8, v9
	v_cvt_pk_bf16_f32 v4, v10, v11
	v_cvt_pk_bf16_f32 v5, v12, v13
	global_store_dwordx4 v[54:55], v[2:5], off offset:2432
	s_barrier
	s_cbranch_scc0 .LBB0_617
